# attention unit latch wait re-derived for 4 output stores (vmcnt 8 to 4) so the next unit's prefetch loads stay covered
# baseline (speedup 1.0000x reference)
.LBB0_385:
	s_or_b64 exec, exec, s[6:7]
	s_waitcnt lgkmcnt(0)
	s_barrier
	s_waitcnt vmcnt(4)
	v_mov_b64_e32 v[60:61], v[128:129]
	v_mov_b64_e32 v[56:57], v[124:125]
	v_mov_b64_e32 v[52:53], v[120:121]
	v_mov_b64_e32 v[48:49], v[116:117]
	s_andn2_b64 vcc, exec, s[74:75]
	v_mov_b64_e32 v[62:63], v[130:131]
	v_mov_b64_e32 v[58:59], v[126:127]
	v_mov_b64_e32 v[54:55], v[122:123]
	v_mov_b64_e32 v[50:51], v[118:119]
	s_mov_b32 s6, s76
	s_mov_b32 s1, s90
	s_mov_b32 s67, s91
	s_mov_b32 s97, s87
	s_mov_b32 s13, s88
	s_mov_b32 s89, s80
	s_mov_b32 s69, s94
	s_mov_b32 s68, s92
	s_mov_b32 s12, s95
	s_mov_b32 s0, s93
	s_mov_b32 s78, s96
	s_cbranch_vccz .LBB0_429

.LBB0_1245:
	s_or_b64 exec, exec, s[4:5]
	s_waitcnt lgkmcnt(0)
	s_barrier
	s_waitcnt vmcnt(4)
	v_mov_b64_e32 v[60:61], v[128:129]
	v_mov_b64_e32 v[56:57], v[124:125]
	v_mov_b64_e32 v[52:53], v[120:121]
	v_mov_b64_e32 v[48:49], v[116:117]
	s_andn2_b64 vcc, exec, s[96:97]
	v_mov_b64_e32 v[62:63], v[130:131]
	v_mov_b64_e32 v[58:59], v[126:127]
	v_mov_b64_e32 v[54:55], v[122:123]
	v_mov_b64_e32 v[50:51], v[118:119]
	s_mov_b32 s4, s40
	s_mov_b32 s1, s84
	s_mov_b32 s65, s85
	s_mov_b32 s79, s70
	s_mov_b32 s7, s80
	s_mov_b32 s81, s69
	s_mov_b32 s67, s90
	s_mov_b32 s66, s86
	s_mov_b32 s6, s91
	s_mov_b32 s0, s87
	s_mov_b32 s74, s68
	s_cbranch_vccz .LBB0_1289

.LBB0_2105:
	s_or_b64 exec, exec, s[4:5]
	s_waitcnt lgkmcnt(0)
	s_barrier
	s_waitcnt vmcnt(4)
	v_mov_b64_e32 v[60:61], v[128:129]
	v_mov_b64_e32 v[56:57], v[124:125]
	v_mov_b64_e32 v[52:53], v[120:121]
	v_mov_b64_e32 v[48:49], v[116:117]
	s_andn2_b64 vcc, exec, s[40:41]
	v_mov_b64_e32 v[62:63], v[130:131]
	v_mov_b64_e32 v[58:59], v[126:127]
	v_mov_b64_e32 v[54:55], v[122:123]
	v_mov_b64_e32 v[50:51], v[118:119]
	s_mov_b32 s4, s74
	s_mov_b32 s1, s84
	s_mov_b32 s65, s85
	s_mov_b32 s93, s79
	s_mov_b32 s7, s80
	s_mov_b32 s81, s68
	s_mov_b32 s67, s90
	s_mov_b32 s66, s86
	s_mov_b32 s6, s91
	s_mov_b32 s0, s87
	s_mov_b32 s92, s70
	s_cbranch_vccz .LBB0_2149

.LBB0_2969:
	s_or_b64 exec, exec, s[4:5]
	s_waitcnt lgkmcnt(0)
	s_barrier
	s_waitcnt vmcnt(4)
	v_mov_b64_e32 v[60:61], v[128:129]
	v_mov_b64_e32 v[56:57], v[124:125]
	v_mov_b64_e32 v[52:53], v[120:121]
	v_mov_b64_e32 v[48:49], v[116:117]
	s_andn2_b64 vcc, exec, s[40:41]
	v_mov_b64_e32 v[62:63], v[130:131]
	v_mov_b64_e32 v[58:59], v[126:127]
	v_mov_b64_e32 v[54:55], v[122:123]
	v_mov_b64_e32 v[50:51], v[118:119]
	s_mov_b32 s4, s50
	s_mov_b32 s1, s72
	s_mov_b32 s53, s73
	s_mov_b32 s81, s69
	s_mov_b32 s9, s70
	s_mov_b32 s82, s71
	s_mov_b32 s55, s78
	s_mov_b32 s54, s74
	s_mov_b32 s8, s79
	s_mov_b32 s0, s75
	s_mov_b32 s83, s80
	s_cbranch_vccz .LBB0_3013
